# A/B docs 7.4: P1 GEMM K loop without per-cluster s_setprio flips, one static s_setprio 1 for waves 4-7
# baseline (speedup 1.0000x reference)
; #define PG8_STAGE(bufoff, gbase, voff) do { _Pragma("unroll") for (int _i = 0; _i < 2; ++_i) \
;         __builtin_amdgcn_global_load_lds((const unsigned*)((const char*)(gbase) + (voff)[_i]), (LAS unsigned*)(lds + (bufoff) + ldsw + _i * 8192), 16, 0, 0); } while (0)
; #define PG8_LDA(dst, b, h) do { _Pragma("unroll") for (int m = 0; m < 4; ++m) _Pragma("unroll") for (int k = 0; k < 2; ++k) dst[m][k] = *(const LAS bf16x8*)(lds + PG8_SA(b, h) + aoff + m * 2048 + k * 1024); } while (0)
; #define PG8_LDB(dst, b, h) do { _Pragma("unroll") for (int n = 0; n < 2; ++n) _Pragma("unroll") for (int k = 0; k < 2; ++k) dst[n][k] = *(const LAS bf16x8*)(lds + PG8_SB(b, h) + boff + n * 2048 + k * 1024); } while (0)
; #define PG8_MMA(ai, bj, At, Bt) do { __builtin_amdgcn_s_setprio(1); _Pragma("unroll") for (int m = 0; m < 4; ++m) _Pragma("unroll") for (int n = 0; n < 2; ++n) _Pragma("unroll") for (int k = 0; k < 2; ++k) \
;         acc[ai][bj][m][n] = __builtin_amdgcn_mfma_f32_16x16x32_bf16(Bt[n][k], At[m][k], acc[ai][bj][m][n], 0, 0, 0); __builtin_amdgcn_s_setprio(0); } while (0)
; #define PG8_WAIT_V(n) asm volatile("s_waitcnt vmcnt(" #n ")" ::: "memory")
; #define PG8_WAIT_L(n) asm volatile("s_waitcnt lgkmcnt(" #n ")" ::: "memory")
; #define PG8_BAR __builtin_amdgcn_s_barrier()
; #define PG8_SCHED __builtin_amdgcn_sched_barrier(0)
; template <class Epi, class Sched, bool ALIGN_EPI, bool SP2, bool BPRE = false>
; __device__ __forceinline__ void gemm_phase(LAS unsigned char* lds, const int pitchA, const int pitchB, const Sched& S, const Epi& E) {
;     ...
;             PG8_LDB(B0, 0, 0); PG8_LDB(B1, 0, 1); PG8_SCHED; PG8_LDA(At, 0, 0); PG8_STAGE(PG8_SA(1, 1), a1 + hstepA, voffA);
;             PG8_WAIT_V(8); PG8_WAIT_L(0); PG8_BAR; PG8_MMA(0, 0, At, B0); PG8_MMA(0, 1, At, B1); PG8_BAR; PG8_SCHED;
;     ...
; #pragma unroll
;         for (int a = 0; a < 2; ++a)
; #pragma unroll
;             for (int b = 0; b < 2; ++b)
; #pragma unroll
;                 for (int m = 0; m < 4; ++m)
; #pragma unroll
;                     for (int n = 0; n < 2; ++n) acc[a][b][m][n] = (f32x4){0.f, 0.f, 0.f, 0.f};
.LBB0_156:
	s_add_u32 s66, s66, 0x100080
	s_addc_u32 s67, s67, 0
	s_add_u32 s5, s68, 0x100
	v_mov_b32_e32 v2, 0
	s_addc_u32 s6, s69, 0
	s_mov_b32 s59, -2
	v_mov_b32_e32 v3, v2
	v_mov_b32_e32 v4, v2
	v_mov_b32_e32 v5, v2
	v_mov_b32_e32 v10, v2
	v_mov_b32_e32 v11, v2
	v_mov_b32_e32 v12, v2
	v_mov_b32_e32 v13, v2
	v_mov_b32_e32 v18, v2
	v_mov_b32_e32 v19, v2
	v_mov_b32_e32 v20, v2
	v_mov_b32_e32 v21, v2
	v_mov_b32_e32 v26, v2
	v_mov_b32_e32 v27, v2
	v_mov_b32_e32 v28, v2
	v_mov_b32_e32 v29, v2
	v_mov_b32_e32 v34, v2
	v_mov_b32_e32 v35, v2
	v_mov_b32_e32 v36, v2
	v_mov_b32_e32 v37, v2
	v_mov_b32_e32 v42, v2
	v_mov_b32_e32 v43, v2
	v_mov_b32_e32 v44, v2
	v_mov_b32_e32 v45, v2
	v_mov_b32_e32 v50, v2
	v_mov_b32_e32 v51, v2
	v_mov_b32_e32 v52, v2
	v_mov_b32_e32 v53, v2
	v_mov_b32_e32 v58, v2
	v_mov_b32_e32 v59, v2
	v_mov_b32_e32 v60, v2
	v_mov_b32_e32 v61, v2
	v_mov_b32_e32 v6, v2
	v_mov_b32_e32 v7, v2
	v_mov_b32_e32 v8, v2
	v_mov_b32_e32 v9, v2
	v_mov_b32_e32 v14, v2
	v_mov_b32_e32 v15, v2
	v_mov_b32_e32 v16, v2
	v_mov_b32_e32 v17, v2
	v_mov_b32_e32 v22, v2
	v_mov_b32_e32 v23, v2
	v_mov_b32_e32 v24, v2
	v_mov_b32_e32 v25, v2
	v_mov_b32_e32 v30, v2
	v_mov_b32_e32 v31, v2
	v_mov_b32_e32 v32, v2
	v_mov_b32_e32 v33, v2
	v_mov_b32_e32 v38, v2
	v_mov_b32_e32 v39, v2
	v_mov_b32_e32 v40, v2
	v_mov_b32_e32 v41, v2
	v_mov_b32_e32 v46, v2
	v_mov_b32_e32 v47, v2
	v_mov_b32_e32 v48, v2
	v_mov_b32_e32 v49, v2
	v_mov_b32_e32 v54, v2
	v_mov_b32_e32 v55, v2
	v_mov_b32_e32 v56, v2
	v_mov_b32_e32 v57, v2
	v_mov_b32_e32 v62, v2
	v_mov_b32_e32 v63, v2
	v_mov_b32_e32 v64, v2
	v_mov_b32_e32 v65, v2
	v_mov_b32_e32 v66, v2
	v_mov_b32_e32 v67, v2
	v_mov_b32_e32 v68, v2
	v_mov_b32_e32 v69, v2
	v_mov_b32_e32 v74, v2
	v_mov_b32_e32 v75, v2
	v_mov_b32_e32 v76, v2
	v_mov_b32_e32 v77, v2
	v_mov_b32_e32 v82, v2
	v_mov_b32_e32 v83, v2
	v_mov_b32_e32 v84, v2
	v_mov_b32_e32 v85, v2
	v_mov_b32_e32 v90, v2
	v_mov_b32_e32 v91, v2
	v_mov_b32_e32 v92, v2
	v_mov_b32_e32 v93, v2
	v_mov_b32_e32 v98, v2
	v_mov_b32_e32 v99, v2
	v_mov_b32_e32 v100, v2
	v_mov_b32_e32 v101, v2
	v_mov_b32_e32 v106, v2
	v_mov_b32_e32 v107, v2
	v_mov_b32_e32 v108, v2
	v_mov_b32_e32 v109, v2
	v_mov_b32_e32 v114, v2
	v_mov_b32_e32 v115, v2
	v_mov_b32_e32 v116, v2
	v_mov_b32_e32 v117, v2
	v_mov_b32_e32 v122, v2
	v_mov_b32_e32 v123, v2
	v_mov_b32_e32 v124, v2
	v_mov_b32_e32 v125, v2
	v_mov_b32_e32 v70, v2
	v_mov_b32_e32 v71, v2
	v_mov_b32_e32 v72, v2
	v_mov_b32_e32 v73, v2
	v_mov_b32_e32 v78, v2
	v_mov_b32_e32 v79, v2
	v_mov_b32_e32 v80, v2
	v_mov_b32_e32 v81, v2
	v_mov_b32_e32 v86, v2
	v_mov_b32_e32 v87, v2
	v_mov_b32_e32 v88, v2
	v_mov_b32_e32 v89, v2
	v_mov_b32_e32 v94, v2
	v_mov_b32_e32 v95, v2
	v_mov_b32_e32 v96, v2
	v_mov_b32_e32 v97, v2
	v_mov_b32_e32 v102, v2
	v_mov_b32_e32 v103, v2
	v_mov_b32_e32 v104, v2
	v_mov_b32_e32 v105, v2
	v_mov_b32_e32 v110, v2
	v_mov_b32_e32 v111, v2
	v_mov_b32_e32 v112, v2
	v_mov_b32_e32 v113, v2
	v_mov_b32_e32 v118, v2
	v_mov_b32_e32 v119, v2
	v_mov_b32_e32 v120, v2
	v_mov_b32_e32 v121, v2
	v_mov_b32_e32 v126, v2
	v_mov_b32_e32 v127, v2
	v_mov_b32_e32 v128, v2
	v_mov_b32_e32 v129, v2
	s_and_b64 vcc, exec, s[52:53]
	s_cbranch_vccnz .Lprio_skip1
	s_setprio 1
.Lprio_skip1:
.LBB0_157:
	ds_read_b128 v[146:149], v158
	ds_read_b128 v[150:153], v158 offset:1024
	ds_read_b128 v[154:157], v158 offset:2048
	ds_read_b128 v[162:165], v158 offset:3072
	ds_read_b128 v[166:169], v159
	ds_read_b128 v[170:173], v159 offset:1024
	ds_read_b128 v[174:177], v159 offset:2048
	ds_read_b128 v[178:181], v159 offset:3072
	s_add_u32 s61, s66, 0xfff00080
	s_addc_u32 s63, s67, -1
	s_cmp_eq_u32 s59, 60
	s_cselect_b32 s71, s55, s63
	s_cselect_b32 s70, s54, s61
	s_cselect_b32 s69, s65, s6
	s_cselect_b32 s68, s64, s5
	v_lshl_add_u64 v[214:215], s[66:67], 0, v[142:143]
	s_add_i32 m0, s83, 0xc000
	ds_read_b128 v[182:185], v160
	ds_read_b128 v[186:189], v160 offset:1024
	ds_read_b128 v[190:193], v160 offset:2048
	ds_read_b128 v[194:197], v160 offset:3072
	ds_read_b128 v[198:201], v160 offset:4096
	ds_read_b128 v[202:205], v160 offset:5120
	ds_read_b128 v[206:209], v160 offset:6144
	ds_read_b128 v[210:213], v160 offset:7168
	global_load_lds_dwordx4 v[214:215], off
	v_lshl_add_u64 v[214:215], s[66:67], 0, v[144:145]
	s_add_i32 m0, s83, 0xe000
	s_nop 0
	global_load_lds_dwordx4 v[214:215], off
	s_waitcnt vmcnt(8)
	s_waitcnt lgkmcnt(0)
	s_barrier

; #define PG8_MMA(ai, bj, At, Bt) do { __builtin_amdgcn_s_setprio(1); _Pragma("unroll") for (int m = 0; m < 4; ++m) _Pragma("unroll") for (int n = 0; n < 2; ++n) _Pragma("unroll") for (int k = 0; k < 2; ++k) \
;         acc[ai][bj][m][n] = __builtin_amdgcn_mfma_f32_16x16x32_bf16(Bt[n][k], At[m][k], acc[ai][bj][m][n], 0, 0, 0); __builtin_amdgcn_s_setprio(0); } while (0)
; #define PG8_WAIT_V(n) asm volatile("s_waitcnt vmcnt(" #n ")" ::: "memory")
; #define PG8_WAIT_L(n) asm volatile("s_waitcnt lgkmcnt(" #n ")" ::: "memory")
; #define PG8_BAR __builtin_amdgcn_s_barrier()
; #define PG8_SCHED __builtin_amdgcn_sched_barrier(0)
; template <class Epi, class Sched, bool ALIGN_EPI, bool SP2, bool BPRE = false>
; __device__ __forceinline__ void gemm_phase(LAS unsigned char* lds, const int pitchA, const int pitchB, const Sched& S, const Epi& E) {
;     ...
;             PG8_WAIT_V(8); PG8_WAIT_L(0); PG8_BAR; PG8_MMA(0, 0, At, B0); PG8_MMA(0, 1, At, B1); PG8_BAR; PG8_SCHED;
	s_waitcnt lgkmcnt(0)
	v_mfma_f32_16x16x32_bf16 v[126:129], v[146:149], v[182:185], v[126:129]
	v_mfma_f32_16x16x32_bf16 v[118:121], v[154:157], v[182:185], v[118:121]
	v_mfma_f32_16x16x32_bf16 v[110:113], v[146:149], v[190:193], v[110:113]
	v_mfma_f32_16x16x32_bf16 v[102:105], v[154:157], v[190:193], v[102:105]
	v_mfma_f32_16x16x32_bf16 v[94:97], v[146:149], v[198:201], v[94:97]
	v_mfma_f32_16x16x32_bf16 v[86:89], v[154:157], v[198:201], v[86:89]
	v_mfma_f32_16x16x32_bf16 v[78:81], v[146:149], v[206:209], v[78:81]
	v_mfma_f32_16x16x32_bf16 v[70:73], v[154:157], v[206:209], v[70:73]
	v_mfma_f32_16x16x32_bf16 v[126:129], v[150:153], v[186:189], v[126:129]
	v_mfma_f32_16x16x32_bf16 v[118:121], v[162:165], v[186:189], v[118:121]
	v_mfma_f32_16x16x32_bf16 v[110:113], v[150:153], v[194:197], v[110:113]
	v_mfma_f32_16x16x32_bf16 v[102:105], v[162:165], v[194:197], v[102:105]
	v_mfma_f32_16x16x32_bf16 v[94:97], v[150:153], v[202:205], v[94:97]
	v_mfma_f32_16x16x32_bf16 v[86:89], v[162:165], v[202:205], v[86:89]
	v_mfma_f32_16x16x32_bf16 v[78:81], v[150:153], v[210:213], v[78:81]
	v_mfma_f32_16x16x32_bf16 v[70:73], v[162:165], v[210:213], v[70:73]


; #define PG8_MMA(ai, bj, At, Bt) do { __builtin_amdgcn_s_setprio(1); _Pragma("unroll") for (int m = 0; m < 4; ++m) _Pragma("unroll") for (int n = 0; n < 2; ++n) _Pragma("unroll") for (int k = 0; k < 2; ++k) \
;         acc[ai][bj][m][n] = __builtin_amdgcn_mfma_f32_16x16x32_bf16(Bt[n][k], At[m][k], acc[ai][bj][m][n], 0, 0, 0); __builtin_amdgcn_s_setprio(0); } while (0)
; #define PG8_WAIT_V(n) asm volatile("s_waitcnt vmcnt(" #n ")" ::: "memory")
; #define PG8_WAIT_L(n) asm volatile("s_waitcnt lgkmcnt(" #n ")" ::: "memory")
; #define PG8_BAR __builtin_amdgcn_s_barrier()
; #define PG8_SCHED __builtin_amdgcn_sched_barrier(0)
; template <class Epi, class Sched, bool ALIGN_EPI, bool SP2, bool BPRE = false>
; __device__ __forceinline__ void gemm_phase(LAS unsigned char* lds, const int pitchA, const int pitchB, const Sched& S, const Epi& E) {
;     ...
;             PG8_WAIT_V(8); PG8_WAIT_L(0); PG8_BAR; PG8_MMA(0, 0, At, B0); PG8_MMA(0, 1, At, B1); PG8_BAR; PG8_SCHED;
	v_mfma_f32_16x16x32_bf16 v[122:125], v[166:169], v[182:185], v[122:125]
	v_mfma_f32_16x16x32_bf16 v[114:117], v[174:177], v[182:185], v[114:117]
	v_mfma_f32_16x16x32_bf16 v[106:109], v[166:169], v[190:193], v[106:109]
	v_mfma_f32_16x16x32_bf16 v[98:101], v[174:177], v[190:193], v[98:101]
	v_mfma_f32_16x16x32_bf16 v[90:93], v[166:169], v[198:201], v[90:93]
	v_mfma_f32_16x16x32_bf16 v[82:85], v[174:177], v[198:201], v[82:85]
	v_mfma_f32_16x16x32_bf16 v[74:77], v[166:169], v[206:209], v[74:77]
	v_mfma_f32_16x16x32_bf16 v[66:69], v[174:177], v[206:209], v[66:69]
	v_mfma_f32_16x16x32_bf16 v[122:125], v[170:173], v[186:189], v[122:125]
	v_mfma_f32_16x16x32_bf16 v[114:117], v[178:181], v[186:189], v[114:117]
	v_mfma_f32_16x16x32_bf16 v[106:109], v[170:173], v[194:197], v[106:109]
	v_mfma_f32_16x16x32_bf16 v[98:101], v[178:181], v[194:197], v[98:101]
	v_mfma_f32_16x16x32_bf16 v[90:93], v[170:173], v[202:205], v[90:93]
	v_mfma_f32_16x16x32_bf16 v[82:85], v[178:181], v[202:205], v[82:85]
	v_mfma_f32_16x16x32_bf16 v[74:77], v[170:173], v[210:213], v[74:77]
	v_mfma_f32_16x16x32_bf16 v[66:69], v[178:181], v[210:213], v[66:69]

; #define PG8_STAGE(bufoff, gbase, voff) do { _Pragma("unroll") for (int _i = 0; _i < 2; ++_i) \
;         __builtin_amdgcn_global_load_lds((const unsigned*)((const char*)(gbase) + (voff)[_i]), (LAS unsigned*)(lds + (bufoff) + ldsw + _i * 8192), 16, 0, 0); } while (0)
; #define PG8_LDA(dst, b, h) do { _Pragma("unroll") for (int m = 0; m < 4; ++m) _Pragma("unroll") for (int k = 0; k < 2; ++k) dst[m][k] = *(const LAS bf16x8*)(lds + PG8_SA(b, h) + aoff + m * 2048 + k * 1024); } while (0)
; #define PG8_MMA(ai, bj, At, Bt) do { __builtin_amdgcn_s_setprio(1); _Pragma("unroll") for (int m = 0; m < 4; ++m) _Pragma("unroll") for (int n = 0; n < 2; ++n) _Pragma("unroll") for (int k = 0; k < 2; ++k) \
;         acc[ai][bj][m][n] = __builtin_amdgcn_mfma_f32_16x16x32_bf16(Bt[n][k], At[m][k], acc[ai][bj][m][n], 0, 0, 0); __builtin_amdgcn_s_setprio(0); } while (0)
; #define PG8_WAIT_V(n) asm volatile("s_waitcnt vmcnt(" #n ")" ::: "memory")
; #define PG8_WAIT_L(n) asm volatile("s_waitcnt lgkmcnt(" #n ")" ::: "memory")
; #define PG8_BAR __builtin_amdgcn_s_barrier()
; #define PG8_SCHED __builtin_amdgcn_sched_barrier(0)
; template <class Epi, class Sched, bool ALIGN_EPI, bool SP2, bool BPRE = false>
; __device__ __forceinline__ void gemm_phase(LAS unsigned char* lds, const int pitchA, const int pitchB, const Sched& S, const Epi& E) {
;     ...
;             PG8_LDA(At, 0, 1); PG8_STAGE(PG8_SB(0, 0), b2, voffB); PG8_STAGE(PG8_SB(0, 1), b2 + hstepB, voffB); PG8_STAGE(PG8_SA(0, 0), a2, voffA);
;             PG8_WAIT_V(8); PG8_WAIT_L(0); PG8_BAR; PG8_MMA(1, 0, At, B0); PG8_MMA(1, 1, At, B1); PG8_BAR; PG8_SCHED;
	s_barrier
	s_add_i32 s61, s90, s82
	v_lshl_add_u64 v[214:215], s[68:69], 0, v[132:133]
	s_mov_b32 m0, s61
	ds_read_b128 v[182:185], v160 offset:16384
	ds_read_b128 v[186:189], v160 offset:17408
	ds_read_b128 v[190:193], v160 offset:18432
	ds_read_b128 v[194:197], v160 offset:19456
	ds_read_b128 v[198:201], v160 offset:20480
	ds_read_b128 v[202:205], v160 offset:21504
	ds_read_b128 v[206:209], v160 offset:22528
	ds_read_b128 v[210:213], v160 offset:23552
	global_load_lds_dwordx4 v[214:215], off
	s_add_i32 m0, s61, 0x2000
	s_add_u32 s72, s68, 0x100000
	v_lshl_add_u64 v[216:217], s[68:69], 0, v[136:137]
	s_addc_u32 s73, s69, 0
	s_add_i32 s61, s91, s82
	global_load_lds_dwordx4 v[216:217], off
	v_lshl_add_u64 v[218:219], s[72:73], 0, v[132:133]
	s_mov_b32 m0, s61
	v_lshl_add_u64 v[220:221], s[70:71], 0, v[134:135]
	global_load_lds_dwordx4 v[218:219], off
	v_lshl_add_u64 v[218:219], s[72:73], 0, v[136:137]
	s_add_i32 m0, s61, 0x2000
	s_nop 0
	global_load_lds_dwordx4 v[218:219], off
	v_lshl_add_u64 v[218:219], s[70:71], 0, v[130:131]
	s_mov_b32 m0, s83
	s_nop 0
	global_load_lds_dwordx4 v[218:219], off
	s_mov_b32 m0, s84
	s_nop 0
	global_load_lds_dwordx4 v[220:221], off
	s_waitcnt vmcnt(8)
	s_waitcnt lgkmcnt(0)
	s_barrier

; #define PG8_MMA(ai, bj, At, Bt) do { __builtin_amdgcn_s_setprio(1); _Pragma("unroll") for (int m = 0; m < 4; ++m) _Pragma("unroll") for (int n = 0; n < 2; ++n) _Pragma("unroll") for (int k = 0; k < 2; ++k) \
;         acc[ai][bj][m][n] = __builtin_amdgcn_mfma_f32_16x16x32_bf16(Bt[n][k], At[m][k], acc[ai][bj][m][n], 0, 0, 0); __builtin_amdgcn_s_setprio(0); } while (0)
; #define PG8_WAIT_V(n) asm volatile("s_waitcnt vmcnt(" #n ")" ::: "memory")
; #define PG8_WAIT_L(n) asm volatile("s_waitcnt lgkmcnt(" #n ")" ::: "memory")
; #define PG8_BAR __builtin_amdgcn_s_barrier()
; #define PG8_SCHED __builtin_amdgcn_sched_barrier(0)
; template <class Epi, class Sched, bool ALIGN_EPI, bool SP2, bool BPRE = false>
; __device__ __forceinline__ void gemm_phase(LAS unsigned char* lds, const int pitchA, const int pitchB, const Sched& S, const Epi& E) {
;     ...
;             PG8_WAIT_V(8); PG8_WAIT_L(0); PG8_BAR; PG8_MMA(1, 0, At, B0); PG8_MMA(1, 1, At, B1); PG8_BAR; PG8_SCHED;
	s_waitcnt lgkmcnt(0)
	v_mfma_f32_16x16x32_bf16 v[62:65], v[146:149], v[182:185], v[62:65]
	v_mfma_f32_16x16x32_bf16 v[54:57], v[154:157], v[182:185], v[54:57]
	v_mfma_f32_16x16x32_bf16 v[46:49], v[146:149], v[190:193], v[46:49]
	v_mfma_f32_16x16x32_bf16 v[38:41], v[154:157], v[190:193], v[38:41]
	v_mfma_f32_16x16x32_bf16 v[30:33], v[146:149], v[198:201], v[30:33]
	v_mfma_f32_16x16x32_bf16 v[22:25], v[154:157], v[198:201], v[22:25]
	v_mfma_f32_16x16x32_bf16 v[14:17], v[146:149], v[206:209], v[14:17]
	v_mfma_f32_16x16x32_bf16 v[6:9], v[154:157], v[206:209], v[6:9]
	v_mfma_f32_16x16x32_bf16 v[62:65], v[150:153], v[186:189], v[62:65]
	v_mfma_f32_16x16x32_bf16 v[54:57], v[162:165], v[186:189], v[54:57]
	v_mfma_f32_16x16x32_bf16 v[46:49], v[150:153], v[194:197], v[46:49]
	v_mfma_f32_16x16x32_bf16 v[38:41], v[162:165], v[194:197], v[38:41]
	v_mfma_f32_16x16x32_bf16 v[30:33], v[150:153], v[202:205], v[30:33]
	v_mfma_f32_16x16x32_bf16 v[22:25], v[162:165], v[202:205], v[22:25]
	v_mfma_f32_16x16x32_bf16 v[14:17], v[150:153], v[210:213], v[14:17]
	v_mfma_f32_16x16x32_bf16 v[6:9], v[162:165], v[210:213], v[6:9]


; #define PG8_MMA(ai, bj, At, Bt) do { __builtin_amdgcn_s_setprio(1); _Pragma("unroll") for (int m = 0; m < 4; ++m) _Pragma("unroll") for (int n = 0; n < 2; ++n) _Pragma("unroll") for (int k = 0; k < 2; ++k) \
;         acc[ai][bj][m][n] = __builtin_amdgcn_mfma_f32_16x16x32_bf16(Bt[n][k], At[m][k], acc[ai][bj][m][n], 0, 0, 0); __builtin_amdgcn_s_setprio(0); } while (0)
; #define PG8_WAIT_V(n) asm volatile("s_waitcnt vmcnt(" #n ")" ::: "memory")
; #define PG8_WAIT_L(n) asm volatile("s_waitcnt lgkmcnt(" #n ")" ::: "memory")
; #define PG8_BAR __builtin_amdgcn_s_barrier()
; #define PG8_SCHED __builtin_amdgcn_sched_barrier(0)
; template <class Epi, class Sched, bool ALIGN_EPI, bool SP2, bool BPRE = false>
; __device__ __forceinline__ void gemm_phase(LAS unsigned char* lds, const int pitchA, const int pitchB, const Sched& S, const Epi& E) {
;     ...
;             PG8_WAIT_V(8); PG8_WAIT_L(0); PG8_BAR; PG8_MMA(1, 0, At, B0); PG8_MMA(1, 1, At, B1); PG8_BAR; PG8_SCHED;
	v_mfma_f32_16x16x32_bf16 v[58:61], v[166:169], v[182:185], v[58:61]
	v_mfma_f32_16x16x32_bf16 v[50:53], v[174:177], v[182:185], v[50:53]
	v_mfma_f32_16x16x32_bf16 v[42:45], v[166:169], v[190:193], v[42:45]
	v_mfma_f32_16x16x32_bf16 v[34:37], v[174:177], v[190:193], v[34:37]
	v_mfma_f32_16x16x32_bf16 v[26:29], v[166:169], v[198:201], v[26:29]
	v_mfma_f32_16x16x32_bf16 v[18:21], v[174:177], v[198:201], v[18:21]
	v_mfma_f32_16x16x32_bf16 v[10:13], v[166:169], v[206:209], v[10:13]
	v_mfma_f32_16x16x32_bf16 v[2:5], v[174:177], v[206:209], v[2:5]
	v_mfma_f32_16x16x32_bf16 v[58:61], v[170:173], v[186:189], v[58:61]
	v_mfma_f32_16x16x32_bf16 v[50:53], v[178:181], v[186:189], v[50:53]
	v_mfma_f32_16x16x32_bf16 v[42:45], v[170:173], v[194:197], v[42:45]
	v_mfma_f32_16x16x32_bf16 v[34:37], v[178:181], v[194:197], v[34:37]
	v_mfma_f32_16x16x32_bf16 v[26:29], v[170:173], v[202:205], v[26:29]
	v_mfma_f32_16x16x32_bf16 v[18:21], v[178:181], v[202:205], v[18:21]
	v_mfma_f32_16x16x32_bf16 v[10:13], v[170:173], v[210:213], v[10:13]
	v_mfma_f32_16x16x32_bf16 v[2:5], v[178:181], v[210:213], v[2:5]

; #define PG8_STAGE(bufoff, gbase, voff) do { _Pragma("unroll") for (int _i = 0; _i < 2; ++_i) \
;         __builtin_amdgcn_global_load_lds((const unsigned*)((const char*)(gbase) + (voff)[_i]), (LAS unsigned*)(lds + (bufoff) + ldsw + _i * 8192), 16, 0, 0); } while (0)
; #define PG8_LDA(dst, b, h) do { _Pragma("unroll") for (int m = 0; m < 4; ++m) _Pragma("unroll") for (int k = 0; k < 2; ++k) dst[m][k] = *(const LAS bf16x8*)(lds + PG8_SA(b, h) + aoff + m * 2048 + k * 1024); } while (0)
; #define PG8_LDB(dst, b, h) do { _Pragma("unroll") for (int n = 0; n < 2; ++n) _Pragma("unroll") for (int k = 0; k < 2; ++k) dst[n][k] = *(const LAS bf16x8*)(lds + PG8_SB(b, h) + boff + n * 2048 + k * 1024); } while (0)
; #define PG8_MMA(ai, bj, At, Bt) do { __builtin_amdgcn_s_setprio(1); _Pragma("unroll") for (int m = 0; m < 4; ++m) _Pragma("unroll") for (int n = 0; n < 2; ++n) _Pragma("unroll") for (int k = 0; k < 2; ++k) \
;         acc[ai][bj][m][n] = __builtin_amdgcn_mfma_f32_16x16x32_bf16(Bt[n][k], At[m][k], acc[ai][bj][m][n], 0, 0, 0); __builtin_amdgcn_s_setprio(0); } while (0)
; #define PG8_WAIT_V(n) asm volatile("s_waitcnt vmcnt(" #n ")" ::: "memory")
; #define PG8_WAIT_L(n) asm volatile("s_waitcnt lgkmcnt(" #n ")" ::: "memory")
; #define PG8_BAR __builtin_amdgcn_s_barrier()
; #define PG8_SCHED __builtin_amdgcn_sched_barrier(0)
; template <class Epi, class Sched, bool ALIGN_EPI, bool SP2, bool BPRE = false>
; __device__ __forceinline__ void gemm_phase(LAS unsigned char* lds, const int pitchA, const int pitchB, const Sched& S, const Epi& E) {
;     ...
;             PG8_LDB(B0, 1, 0); PG8_LDB(B1, 1, 1); PG8_SCHED; PG8_LDA(At, 1, 0); PG8_STAGE(PG8_SA(0, 1), a2 + hstepA, voffA);
;             PG8_WAIT_V(8); PG8_WAIT_L(0); PG8_BAR; PG8_MMA(0, 0, At, B0); PG8_MMA(0, 1, At, B1); PG8_BAR; PG8_SCHED;
	s_barrier
	s_add_i32 s61, 0, 0x18000
	v_add_u32_e32 v138, s61, v141
	s_add_i32 s63, 0, 0x1c000
	ds_read_b128 v[146:149], v138
	ds_read_b128 v[150:153], v138 offset:1024
	ds_read_b128 v[154:157], v138 offset:2048
	ds_read_b128 v[162:165], v138 offset:3072
	v_add_u32_e32 v138, s63, v141
	ds_read_b128 v[166:169], v138
	ds_read_b128 v[170:173], v138 offset:1024
	ds_read_b128 v[174:177], v138 offset:2048
	ds_read_b128 v[178:181], v138 offset:3072
	s_add_u32 s70, s70, 0x100000
	s_addc_u32 s71, s71, 0
	s_mov_b32 m0, s85
	v_lshl_add_u64 v[222:223], s[70:71], 0, v[130:131]
	ds_read_b128 v[182:185], v160 offset:32768
	ds_read_b128 v[186:189], v160 offset:33792
	ds_read_b128 v[190:193], v160 offset:34816
	ds_read_b128 v[194:197], v160 offset:35840
	ds_read_b128 v[198:201], v160 offset:36864
	ds_read_b128 v[202:205], v160 offset:37888
	ds_read_b128 v[206:209], v160 offset:38912
	ds_read_b128 v[210:213], v160 offset:39936
	global_load_lds_dwordx4 v[222:223], off
	v_lshl_add_u64 v[222:223], s[70:71], 0, v[134:135]
	s_mov_b32 m0, s86
	s_nop 0
	global_load_lds_dwordx4 v[222:223], off
	s_waitcnt vmcnt(8)
	s_waitcnt lgkmcnt(0)
	s_barrier

; #define PG8_MMA(ai, bj, At, Bt) do { __builtin_amdgcn_s_setprio(1); _Pragma("unroll") for (int m = 0; m < 4; ++m) _Pragma("unroll") for (int n = 0; n < 2; ++n) _Pragma("unroll") for (int k = 0; k < 2; ++k) \
;         acc[ai][bj][m][n] = __builtin_amdgcn_mfma_f32_16x16x32_bf16(Bt[n][k], At[m][k], acc[ai][bj][m][n], 0, 0, 0); __builtin_amdgcn_s_setprio(0); } while (0)
; #define PG8_WAIT_V(n) asm volatile("s_waitcnt vmcnt(" #n ")" ::: "memory")
; #define PG8_WAIT_L(n) asm volatile("s_waitcnt lgkmcnt(" #n ")" ::: "memory")
; #define PG8_BAR __builtin_amdgcn_s_barrier()
; #define PG8_SCHED __builtin_amdgcn_sched_barrier(0)
; template <class Epi, class Sched, bool ALIGN_EPI, bool SP2, bool BPRE = false>
; __device__ __forceinline__ void gemm_phase(LAS unsigned char* lds, const int pitchA, const int pitchB, const Sched& S, const Epi& E) {
;     ...
;             PG8_WAIT_V(8); PG8_WAIT_L(0); PG8_BAR; PG8_MMA(0, 0, At, B0); PG8_MMA(0, 1, At, B1); PG8_BAR; PG8_SCHED;
	s_waitcnt lgkmcnt(0)
	v_mfma_f32_16x16x32_bf16 v[126:129], v[146:149], v[182:185], v[126:129]
	v_mfma_f32_16x16x32_bf16 v[118:121], v[154:157], v[182:185], v[118:121]
	v_mfma_f32_16x16x32_bf16 v[110:113], v[146:149], v[190:193], v[110:113]
	v_mfma_f32_16x16x32_bf16 v[102:105], v[154:157], v[190:193], v[102:105]
	v_mfma_f32_16x16x32_bf16 v[94:97], v[146:149], v[198:201], v[94:97]
	v_mfma_f32_16x16x32_bf16 v[86:89], v[154:157], v[198:201], v[86:89]
	v_mfma_f32_16x16x32_bf16 v[78:81], v[146:149], v[206:209], v[78:81]
	v_mfma_f32_16x16x32_bf16 v[70:73], v[154:157], v[206:209], v[70:73]
	v_mfma_f32_16x16x32_bf16 v[126:129], v[150:153], v[186:189], v[126:129]
	v_mfma_f32_16x16x32_bf16 v[118:121], v[162:165], v[186:189], v[118:121]
	v_mfma_f32_16x16x32_bf16 v[110:113], v[150:153], v[194:197], v[110:113]
	v_mfma_f32_16x16x32_bf16 v[102:105], v[162:165], v[194:197], v[102:105]
	v_mfma_f32_16x16x32_bf16 v[94:97], v[150:153], v[202:205], v[94:97]
	v_mfma_f32_16x16x32_bf16 v[86:89], v[162:165], v[202:205], v[86:89]
	v_mfma_f32_16x16x32_bf16 v[78:81], v[150:153], v[210:213], v[78:81]
	v_mfma_f32_16x16x32_bf16 v[70:73], v[162:165], v[210:213], v[70:73]


; #define PG8_MMA(ai, bj, At, Bt) do { __builtin_amdgcn_s_setprio(1); _Pragma("unroll") for (int m = 0; m < 4; ++m) _Pragma("unroll") for (int n = 0; n < 2; ++n) _Pragma("unroll") for (int k = 0; k < 2; ++k) \
;         acc[ai][bj][m][n] = __builtin_amdgcn_mfma_f32_16x16x32_bf16(Bt[n][k], At[m][k], acc[ai][bj][m][n], 0, 0, 0); __builtin_amdgcn_s_setprio(0); } while (0)
; #define PG8_WAIT_V(n) asm volatile("s_waitcnt vmcnt(" #n ")" ::: "memory")
; #define PG8_WAIT_L(n) asm volatile("s_waitcnt lgkmcnt(" #n ")" ::: "memory")
; #define PG8_BAR __builtin_amdgcn_s_barrier()
; #define PG8_SCHED __builtin_amdgcn_sched_barrier(0)
; template <class Epi, class Sched, bool ALIGN_EPI, bool SP2, bool BPRE = false>
; __device__ __forceinline__ void gemm_phase(LAS unsigned char* lds, const int pitchA, const int pitchB, const Sched& S, const Epi& E) {
;     ...
;             PG8_WAIT_V(8); PG8_WAIT_L(0); PG8_BAR; PG8_MMA(0, 0, At, B0); PG8_MMA(0, 1, At, B1); PG8_BAR; PG8_SCHED;
	v_mfma_f32_16x16x32_bf16 v[122:125], v[166:169], v[182:185], v[122:125]
	v_mfma_f32_16x16x32_bf16 v[114:117], v[174:177], v[182:185], v[114:117]
	v_mfma_f32_16x16x32_bf16 v[106:109], v[166:169], v[190:193], v[106:109]
	v_mfma_f32_16x16x32_bf16 v[98:101], v[174:177], v[190:193], v[98:101]
	v_mfma_f32_16x16x32_bf16 v[90:93], v[166:169], v[198:201], v[90:93]
	v_mfma_f32_16x16x32_bf16 v[82:85], v[174:177], v[198:201], v[82:85]
	v_mfma_f32_16x16x32_bf16 v[74:77], v[166:169], v[206:209], v[74:77]
	v_mfma_f32_16x16x32_bf16 v[66:69], v[174:177], v[206:209], v[66:69]
	v_mfma_f32_16x16x32_bf16 v[122:125], v[170:173], v[186:189], v[122:125]
	v_mfma_f32_16x16x32_bf16 v[114:117], v[178:181], v[186:189], v[114:117]
	v_mfma_f32_16x16x32_bf16 v[106:109], v[170:173], v[194:197], v[106:109]
	v_mfma_f32_16x16x32_bf16 v[98:101], v[178:181], v[194:197], v[98:101]
	v_mfma_f32_16x16x32_bf16 v[90:93], v[170:173], v[202:205], v[90:93]
	v_mfma_f32_16x16x32_bf16 v[82:85], v[178:181], v[202:205], v[82:85]
	v_mfma_f32_16x16x32_bf16 v[74:77], v[170:173], v[210:213], v[74:77]
	v_mfma_f32_16x16x32_bf16 v[66:69], v[178:181], v[210:213], v[66:69]

; #define PG8_STAGE(bufoff, gbase, voff) do { _Pragma("unroll") for (int _i = 0; _i < 2; ++_i) \
;         __builtin_amdgcn_global_load_lds((const unsigned*)((const char*)(gbase) + (voff)[_i]), (LAS unsigned*)(lds + (bufoff) + ldsw + _i * 8192), 16, 0, 0); } while (0)
; #define PG8_LDA(dst, b, h) do { _Pragma("unroll") for (int m = 0; m < 4; ++m) _Pragma("unroll") for (int k = 0; k < 2; ++k) dst[m][k] = *(const LAS bf16x8*)(lds + PG8_SA(b, h) + aoff + m * 2048 + k * 1024); } while (0)
; #define PG8_MMA(ai, bj, At, Bt) do { __builtin_amdgcn_s_setprio(1); _Pragma("unroll") for (int m = 0; m < 4; ++m) _Pragma("unroll") for (int n = 0; n < 2; ++n) _Pragma("unroll") for (int k = 0; k < 2; ++k) \
;         acc[ai][bj][m][n] = __builtin_amdgcn_mfma_f32_16x16x32_bf16(Bt[n][k], At[m][k], acc[ai][bj][m][n], 0, 0, 0); __builtin_amdgcn_s_setprio(0); } while (0)
; #define PG8_WAIT_V(n) asm volatile("s_waitcnt vmcnt(" #n ")" ::: "memory")
; #define PG8_WAIT_L(n) asm volatile("s_waitcnt lgkmcnt(" #n ")" ::: "memory")
; #define PG8_BAR __builtin_amdgcn_s_barrier()
; #define PG8_SCHED __builtin_amdgcn_sched_barrier(0)
; template <class Epi, class Sched, bool ALIGN_EPI, bool SP2, bool BPRE = false>
; __device__ __forceinline__ void gemm_phase(LAS unsigned char* lds, const int pitchA, const int pitchB, const Sched& S, const Epi& E) {
;     ...
;             PG8_LDA(At, 1, 1); PG8_STAGE(PG8_SB(1, 0), b3, voffB); PG8_STAGE(PG8_SB(1, 1), b3 + hstepB, voffB); PG8_STAGE(PG8_SA(1, 0), a3, voffA);
;             PG8_WAIT_V(8); PG8_WAIT_L(0); PG8_BAR; PG8_MMA(1, 0, At, B0); PG8_MMA(1, 1, At, B1); PG8_BAR; PG8_SCHED;
	s_barrier
	s_add_i32 s61, s61, s82
	v_lshl_add_u64 v[214:215], v[214:215], 0, s[50:51]
	s_mov_b32 m0, s61
	ds_read_b128 v[182:185], v160 offset:49152
	ds_read_b128 v[186:189], v160 offset:50176
	ds_read_b128 v[190:193], v160 offset:51200
	ds_read_b128 v[194:197], v160 offset:52224
	ds_read_b128 v[198:201], v160 offset:53248
	ds_read_b128 v[202:205], v160 offset:54272
	ds_read_b128 v[206:209], v160 offset:55296
	ds_read_b128 v[210:213], v160 offset:56320
	global_load_lds_dwordx4 v[214:215], off
	s_add_i32 m0, s61, 0x2000
	s_add_u32 s68, s68, 0x100080
	v_lshl_add_u64 v[214:215], v[216:217], 0, s[50:51]
	s_addc_u32 s69, s69, 0
	s_add_i32 s61, s63, s82
	global_load_lds_dwordx4 v[214:215], off
	v_lshl_add_u64 v[214:215], s[68:69], 0, v[132:133]
	s_mov_b32 m0, s61
	s_nop 0
	global_load_lds_dwordx4 v[214:215], off
	v_lshl_add_u64 v[214:215], s[68:69], 0, v[136:137]
	s_add_i32 m0, s61, 0x2000
	s_nop 0
	global_load_lds_dwordx4 v[214:215], off
	v_lshl_add_u64 v[214:215], v[218:219], 0, s[50:51]
	s_mov_b32 m0, s88
	s_nop 0
	global_load_lds_dwordx4 v[214:215], off
	v_lshl_add_u64 v[214:215], v[220:221], 0, s[50:51]
	s_mov_b32 m0, s89
	s_nop 0
	global_load_lds_dwordx4 v[214:215], off
	s_waitcnt vmcnt(8)
	s_waitcnt lgkmcnt(0)
	s_barrier

; #define PG8_MMA(ai, bj, At, Bt) do { __builtin_amdgcn_s_setprio(1); _Pragma("unroll") for (int m = 0; m < 4; ++m) _Pragma("unroll") for (int n = 0; n < 2; ++n) _Pragma("unroll") for (int k = 0; k < 2; ++k) \
;         acc[ai][bj][m][n] = __builtin_amdgcn_mfma_f32_16x16x32_bf16(Bt[n][k], At[m][k], acc[ai][bj][m][n], 0, 0, 0); __builtin_amdgcn_s_setprio(0); } while (0)
; #define PG8_WAIT_V(n) asm volatile("s_waitcnt vmcnt(" #n ")" ::: "memory")
; #define PG8_WAIT_L(n) asm volatile("s_waitcnt lgkmcnt(" #n ")" ::: "memory")
; #define PG8_BAR __builtin_amdgcn_s_barrier()
; #define PG8_SCHED __builtin_amdgcn_sched_barrier(0)
; template <class Epi, class Sched, bool ALIGN_EPI, bool SP2, bool BPRE = false>
; __device__ __forceinline__ void gemm_phase(LAS unsigned char* lds, const int pitchA, const int pitchB, const Sched& S, const Epi& E) {
;     ...
;             PG8_WAIT_V(8); PG8_WAIT_L(0); PG8_BAR; PG8_MMA(1, 0, At, B0); PG8_MMA(1, 1, At, B1); PG8_BAR; PG8_SCHED;
	s_waitcnt lgkmcnt(0)
	v_mfma_f32_16x16x32_bf16 v[62:65], v[146:149], v[182:185], v[62:65]
	v_mfma_f32_16x16x32_bf16 v[54:57], v[154:157], v[182:185], v[54:57]
	v_mfma_f32_16x16x32_bf16 v[46:49], v[146:149], v[190:193], v[46:49]
	v_mfma_f32_16x16x32_bf16 v[38:41], v[154:157], v[190:193], v[38:41]
	v_mfma_f32_16x16x32_bf16 v[30:33], v[146:149], v[198:201], v[30:33]
	v_mfma_f32_16x16x32_bf16 v[22:25], v[154:157], v[198:201], v[22:25]
	v_mfma_f32_16x16x32_bf16 v[14:17], v[146:149], v[206:209], v[14:17]
	v_mfma_f32_16x16x32_bf16 v[6:9], v[154:157], v[206:209], v[6:9]
	v_mfma_f32_16x16x32_bf16 v[62:65], v[150:153], v[186:189], v[62:65]
	v_mfma_f32_16x16x32_bf16 v[54:57], v[162:165], v[186:189], v[54:57]
	v_mfma_f32_16x16x32_bf16 v[46:49], v[150:153], v[194:197], v[46:49]
	v_mfma_f32_16x16x32_bf16 v[38:41], v[162:165], v[194:197], v[38:41]
	v_mfma_f32_16x16x32_bf16 v[30:33], v[150:153], v[202:205], v[30:33]
	v_mfma_f32_16x16x32_bf16 v[22:25], v[162:165], v[202:205], v[22:25]
	v_mfma_f32_16x16x32_bf16 v[14:17], v[150:153], v[210:213], v[14:17]
	v_mfma_f32_16x16x32_bf16 v[6:9], v[162:165], v[210:213], v[6:9]


; #define PG8_MMA(ai, bj, At, Bt) do { __builtin_amdgcn_s_setprio(1); _Pragma("unroll") for (int m = 0; m < 4; ++m) _Pragma("unroll") for (int n = 0; n < 2; ++n) _Pragma("unroll") for (int k = 0; k < 2; ++k) \
;         acc[ai][bj][m][n] = __builtin_amdgcn_mfma_f32_16x16x32_bf16(Bt[n][k], At[m][k], acc[ai][bj][m][n], 0, 0, 0); __builtin_amdgcn_s_setprio(0); } while (0)
; #define PG8_WAIT_V(n) asm volatile("s_waitcnt vmcnt(" #n ")" ::: "memory")
; #define PG8_WAIT_L(n) asm volatile("s_waitcnt lgkmcnt(" #n ")" ::: "memory")
; #define PG8_BAR __builtin_amdgcn_s_barrier()
; #define PG8_SCHED __builtin_amdgcn_sched_barrier(0)
; template <class Epi, class Sched, bool ALIGN_EPI, bool SP2, bool BPRE = false>
; __device__ __forceinline__ void gemm_phase(LAS unsigned char* lds, const int pitchA, const int pitchB, const Sched& S, const Epi& E) {
;     ...
;             PG8_WAIT_V(8); PG8_WAIT_L(0); PG8_BAR; PG8_MMA(1, 0, At, B0); PG8_MMA(1, 1, At, B1); PG8_BAR; PG8_SCHED;
	v_mfma_f32_16x16x32_bf16 v[58:61], v[166:169], v[182:185], v[58:61]
	v_mfma_f32_16x16x32_bf16 v[50:53], v[174:177], v[182:185], v[50:53]
	v_mfma_f32_16x16x32_bf16 v[42:45], v[166:169], v[190:193], v[42:45]
	v_mfma_f32_16x16x32_bf16 v[34:37], v[174:177], v[190:193], v[34:37]
	v_mfma_f32_16x16x32_bf16 v[26:29], v[166:169], v[198:201], v[26:29]
	v_mfma_f32_16x16x32_bf16 v[18:21], v[174:177], v[198:201], v[18:21]
	v_mfma_f32_16x16x32_bf16 v[10:13], v[166:169], v[206:209], v[10:13]
	v_mfma_f32_16x16x32_bf16 v[2:5], v[174:177], v[206:209], v[2:5]
	v_mfma_f32_16x16x32_bf16 v[58:61], v[170:173], v[186:189], v[58:61]
	v_mfma_f32_16x16x32_bf16 v[50:53], v[178:181], v[186:189], v[50:53]
	v_mfma_f32_16x16x32_bf16 v[42:45], v[170:173], v[194:197], v[42:45]
	v_mfma_f32_16x16x32_bf16 v[34:37], v[178:181], v[194:197], v[34:37]
	v_mfma_f32_16x16x32_bf16 v[26:29], v[170:173], v[202:205], v[26:29]
	v_mfma_f32_16x16x32_bf16 v[18:21], v[178:181], v[202:205], v[18:21]
	v_mfma_f32_16x16x32_bf16 v[10:13], v[170:173], v[210:213], v[10:13]
	v_mfma_f32_16x16x32_bf16 v[2:5], v[178:181], v[210:213], v[2:5]

; #define PG8_BAR __builtin_amdgcn_s_barrier()
; template <class Epi, class Sched, bool ALIGN_EPI, bool SP2, bool BPRE = false>
; __device__ __forceinline__ void gemm_phase(LAS unsigned char* lds, const int pitchA, const int pitchB, const Sched& S, const Epi& E) {
;     ...
;         for (int t = 0; t < nt; t += 2) {
;             const bool last = (t == nt - 2);
;             const char* a1 = cA + (size_t)(t + 1) * kstep;
;             const char* a2 = last ? nA : cA + (size_t)(t + 2) * kstep; const char* b2 = last ? nB : cB + (size_t)(t + 2) * kstep;
;     ...
;         if constexpr (ALIGN_EPI) { if (wr == 0) PG8_BAR; }
	s_barrier
	s_add_i32 s59, s59, 2
	s_add_u32 s66, s66, 0x100
	s_addc_u32 s67, s67, 0
	s_add_u32 s5, s5, 0x100
	s_addc_u32 s6, s6, 0
	s_cmp_gt_u32 s59, 61
	s_cbranch_scc0 .LBB0_157
	s_setprio 0
	s_and_b64 vcc, exec, s[52:53]
	s_cbranch_vccz .LBB0_160
	s_barrier
